# v057 + W_IN: the 128 workgroups that have only 13 units start about half a unit late (s_sleep), so the two halves of the chip alternate K-loop and epilogue
# baseline (speedup 1.0000x reference)
.LBB0_194:
	s_cmp_lt_u32 s84, 0x80
	s_cbranch_scc1 .Lwin_nodelay
	s_cmp_eq_u32 s4, 3
	s_cbranch_scc1 .Lwin_nodelay
	s_sleep 120
	s_sleep 120
	s_sleep 120
	s_sleep 120
